# v111 + fixup phase: four late tap/bias loads issued together with one counted wait instead of three serialized round trips
# baseline (speedup 1.0000x reference)
.LBB0_192:
	s_or_b64 exec, exec, s[0:1]
	v_add_u32_e32 v30, 0xb00, v0
	v_lshlrev_b64 v[2:3], 2, v[30:31]
	v_lshl_add_u64 v[4:5], s[8:9], 0, v[2:3]
	v_lshl_add_u64 v[2:3], s[6:7], 0, v[2:3]
	global_load_dword v7, v[4:5], off
	global_load_dword v28, v[2:3], off
	v_add_co_u32_e32 v4, vcc, 0x5000, v2
	s_nop 1
	v_addc_co_u32_e32 v5, vcc, 0, v3, vcc
	v_add_co_u32_e32 v2, vcc, 0xb000, v2
	global_load_dword v26, v[4:5], off offset:2048
	s_nop 0
	v_addc_co_u32_e32 v3, vcc, 0, v3, vcc
	global_load_dword v27, v[2:3], off
	s_waitcnt vmcnt(4)
	v_fmac_f32_e32 v14, v22, v15
	v_fmac_f32_e32 v14, v21, v23
	v_fmac_f32_e32 v14, v20, v24
	v_add_u32_e32 v17, s18, v17
	s_waitcnt vmcnt(0)
	v_fmac_f32_e32 v7, v6, v28
	v_pk_mul_f32 v[2:3], v[8:9], v[26:27]
	s_nop 0
	v_add_f32_e32 v2, v7, v2
	v_add_f32_e32 v2, v2, v3
	v_mul_f32_e32 v3, 0xbfb8aa3b, v14
	v_exp_f32_e32 v3, v3
	s_nop 0
	v_add_f32_e32 v3, 1.0, v3
	v_div_scale_f32 v4, s[0:1], v3, v3, 1.0
	v_rcp_f32_e32 v5, v4
	s_movk_i32 s0, 0x7fff
	v_fma_f32 v6, -v4, v5, 1.0
	v_fmac_f32_e32 v5, v6, v5
	v_div_scale_f32 v6, vcc, 1.0, v3, 1.0
	v_mul_f32_e32 v7, v6, v5
	v_fma_f32 v8, -v4, v7, v6
	v_fmac_f32_e32 v7, v8, v5
	v_fma_f32 v4, -v4, v7, v6
	v_div_fmas_f32 v4, v4, v5, v7
	v_div_fixup_f32 v3, v4, v3, 1.0
	v_mul_f32_e32 v3, v14, v3
	v_mul_f32_e32 v2, v3, v2
	v_bfe_u32 v3, v2, 16, 1
	v_add3_u32 v4, v2, v3, s0
	v_lshl_or_b32 v5, v18, 6, v19
	v_mov_b64_e32 v[2:3], s[34:35]
	s_movk_i32 s0, 0x3080
	v_mad_i64_i32 v[2:3], s[0:1], v5, s0, v[2:3]
	v_readlane_b32 s0, v251, 29
	v_lshl_add_u64 v[0:1], v[0:1], 1, v[2:3]
	global_store_short_d16_hi v[0:1], v4, off offset:2048
	v_add_u32_e32 v16, s0, v16
	s_mov_b32 s0, 0x15ffff
	v_cmp_lt_i32_e32 vcc, s0, v16
	s_or_b64 s[10:11], vcc, s[10:11]
	s_andn2_b64 exec, exec, s[10:11]
	s_cbranch_execz .LBB0_209
